# grid barrier: each XCD leader posts directly on 16 per-XCC release words (no cross-XCD counter), workgroups poll only their own XCC's word (32 pollers per word instead of 256)
# speedup vs baseline: 1.0154x; 1.0051x over previous
; __device__ __forceinline__ unsigned xb_ld(unsigned* p)              { return __hip_atomic_load(p, __ATOMIC_RELAXED, __HIP_MEMORY_SCOPE_AGENT); }
; __device__ __forceinline__ unsigned xb_add(unsigned* p, unsigned v) { return __hip_atomic_fetch_add(p, v, __ATOMIC_RELAXED, __HIP_MEMORY_SCOPE_AGENT); }
; #define XB_SPIN(cond, bar) do { unsigned _sp = 0; while (cond) { __builtin_amdgcn_s_sleep(1); \
;     if ((++_sp & 255u) == 0u) { if (xb_ld(&(bar)[XB_TMO])) break; if (_sp > XB_SPIN_CAP) { atomicAdd(&(bar)[XB_TMO], 1u); break; } } } } while (0)
; __device__ __forceinline__ void xcd_barrier(const XcdBarrier& b) {
;     asm volatile("s_waitcnt vmcnt(0)" ::: "memory");
;     __syncthreads();
;     if (threadIdx.x == 0) {
;         unsigned* bar = b.bar;
;         __builtin_amdgcn_s_waitcnt(0);
;         unsigned nloc = b.st[0], nx = b.st[1];
;         if (nloc == 0u) { xcd_barrier_complete(bar, b.x, nloc, nx); b.st[0] = nloc; b.st[1] = nx; }
;         const unsigned old = xb_add(&bar[XB_XSUB(b.x)], 1u);
;         const unsigned gen = old / nloc;
;         if (old + 1u == (gen + 1u) * nloc) {
;             __builtin_amdgcn_fence(__ATOMIC_RELEASE, "agent");
;             asm volatile("s_waitcnt vmcnt(0)" ::: "memory");
;             const unsigned og = xb_add(&bar[XB_TOP], 1u);
;             const unsigned tg = og / nx;
;             if (og + 1u == (tg + 1u) * nx) xb_add(&bar[XB_TOPGEN], 1u);
;             else XB_SPIN(xb_ld(&bar[XB_TOPGEN]) == tg, bar);
;             __builtin_amdgcn_fence(__ATOMIC_ACQUIRE, "agent");
;             xb_add(&bar[XB_XGEN(b.x)], 1u);
;             asm volatile("s_waitcnt vmcnt(0)" ::: "memory");
;         } else {
;             XB_SPIN(xb_ld(&bar[XB_XGEN(b.x)]) == gen, bar);
;             __builtin_amdgcn_fence(__ATOMIC_ACQUIRE, "agent");
;             asm volatile("s_waitcnt vmcnt(0)" ::: "memory");
;         }
;     }
;     __syncthreads();
; }
.LBB0_59:
	s_lshl_b32 s0, s33, 8
	v_readlane_b32 s4, v255, 1
	v_readlane_b32 s5, v255, 2
	s_add_u32 s10, s4, s0
	s_addc_u32 s11, s5, 0
	v_mov_b32_e32 v3, 0x1000
	v_mov_b32_e32 v4, 1
	global_atomic_add v3, v3, v4, s[10:11] offset:1024 sc0
	s_waitcnt lgkmcnt(0)
	v_readfirstlane_b32 s12, v2
	v_readfirstlane_b32 s13, v0
	s_mul_i32 s12, s12, 1
	s_mul_i32 s13, s13, 1
	v_mov_b32_e32 v1, 0xa2400
	v_mov_b32_e32 v6, 0x2400
	s_mov_b32 s1, 0
	s_waitcnt vmcnt(0)
	v_readfirstlane_b32 s0, v3
	s_add_i32 s0, s0, 1
	s_cmp_lg_u32 s0, s12
	s_cbranch_scc1 .Lgb1_poll
	global_atomic_add v1, v4, s[24:25] offset:0
	global_atomic_add v1, v4, s[24:25] offset:256
	global_atomic_add v1, v4, s[24:25] offset:512
	global_atomic_add v1, v4, s[24:25] offset:768
	global_atomic_add v1, v4, s[24:25] offset:1024
	global_atomic_add v1, v4, s[24:25] offset:1280
	global_atomic_add v1, v4, s[24:25] offset:1536
	global_atomic_add v1, v4, s[24:25] offset:1792
	global_atomic_add v1, v4, s[24:25] offset:2048
	global_atomic_add v1, v4, s[24:25] offset:2304
	global_atomic_add v1, v4, s[24:25] offset:2560
	global_atomic_add v1, v4, s[24:25] offset:2816
	global_atomic_add v1, v4, s[24:25] offset:3072
	global_atomic_add v1, v4, s[24:25] offset:3328
	global_atomic_add v1, v4, s[24:25] offset:3584
	global_atomic_add v1, v4, s[24:25] offset:3840
.Lgb1_poll:
	global_load_dword v5, v6, s[10:11] sc1
	s_add_i32 s1, s1, 1
	s_waitcnt vmcnt(0)
	v_readfirstlane_b32 s0, v5
	s_cmp_ge_u32 s0, s13
	s_cbranch_scc1 .Lgb1_done
	s_cmp_gt_u32 s1, 0x40000
	s_cbranch_scc1 .Lgb1_done
	s_sleep 1
	s_branch .Lgb1_poll

; __device__ __forceinline__ unsigned xb_ld(unsigned* p)              { return __hip_atomic_load(p, __ATOMIC_RELAXED, __HIP_MEMORY_SCOPE_AGENT); }
; __device__ __forceinline__ unsigned xb_add(unsigned* p, unsigned v) { return __hip_atomic_fetch_add(p, v, __ATOMIC_RELAXED, __HIP_MEMORY_SCOPE_AGENT); }
; #define XB_SPIN(cond, bar) do { unsigned _sp = 0; while (cond) { __builtin_amdgcn_s_sleep(1); \
;     if ((++_sp & 255u) == 0u) { if (xb_ld(&(bar)[XB_TMO])) break; if (_sp > XB_SPIN_CAP) { atomicAdd(&(bar)[XB_TMO], 1u); break; } } } } while (0)
; __device__ __forceinline__ void xcd_barrier(const XcdBarrier& b) {
;     ...
;         const unsigned old = xb_add(&bar[XB_XSUB(b.x)], 1u);
;         const unsigned gen = old / nloc;
;         if (old + 1u == (gen + 1u) * nloc) {
;             __builtin_amdgcn_fence(__ATOMIC_RELEASE, "agent");
;             asm volatile("s_waitcnt vmcnt(0)" ::: "memory");
;             const unsigned og = xb_add(&bar[XB_TOP], 1u);
;             const unsigned tg = og / nx;
;             if (og + 1u == (tg + 1u) * nx) xb_add(&bar[XB_TOPGEN], 1u);
;             else XB_SPIN(xb_ld(&bar[XB_TOPGEN]) == tg, bar);
;             __builtin_amdgcn_fence(__ATOMIC_ACQUIRE, "agent");
;             xb_add(&bar[XB_XGEN(b.x)], 1u);
;             asm volatile("s_waitcnt vmcnt(0)" ::: "memory");
;         } else {
;             XB_SPIN(xb_ld(&bar[XB_XGEN(b.x)]) == gen, bar);
;             __builtin_amdgcn_fence(__ATOMIC_ACQUIRE, "agent");
;             asm volatile("s_waitcnt vmcnt(0)" ::: "memory");
;         }
.LBB0_217:
	s_lshl_b32 s0, s33, 8
	v_readlane_b32 s4, v255, 1
	v_readlane_b32 s5, v255, 2
	s_add_u32 s10, s4, s0
	s_addc_u32 s11, s5, 0
	v_mov_b32_e32 v3, 0x1000
	v_mov_b32_e32 v4, 1
	global_atomic_add v3, v3, v4, s[10:11] offset:1024 sc0
	s_waitcnt lgkmcnt(0)
	v_readfirstlane_b32 s12, v2
	v_readfirstlane_b32 s13, v0
	s_mul_i32 s12, s12, 2
	s_mul_i32 s13, s13, 2
	v_mov_b32_e32 v1, 0xa2400
	v_mov_b32_e32 v6, 0x2400
	s_mov_b32 s1, 0
	s_waitcnt vmcnt(0)
	v_readfirstlane_b32 s0, v3
	s_add_i32 s0, s0, 1
	s_cmp_lg_u32 s0, s12
	s_cbranch_scc1 .Lgb2_poll
	global_atomic_add v1, v4, s[24:25] offset:0
	global_atomic_add v1, v4, s[24:25] offset:256
	global_atomic_add v1, v4, s[24:25] offset:512
	global_atomic_add v1, v4, s[24:25] offset:768
	global_atomic_add v1, v4, s[24:25] offset:1024
	global_atomic_add v1, v4, s[24:25] offset:1280
	global_atomic_add v1, v4, s[24:25] offset:1536
	global_atomic_add v1, v4, s[24:25] offset:1792
	global_atomic_add v1, v4, s[24:25] offset:2048
	global_atomic_add v1, v4, s[24:25] offset:2304
	global_atomic_add v1, v4, s[24:25] offset:2560
	global_atomic_add v1, v4, s[24:25] offset:2816
	global_atomic_add v1, v4, s[24:25] offset:3072
	global_atomic_add v1, v4, s[24:25] offset:3328
	global_atomic_add v1, v4, s[24:25] offset:3584
	global_atomic_add v1, v4, s[24:25] offset:3840

; __device__ __forceinline__ unsigned xb_ld(unsigned* p)              { return __hip_atomic_load(p, __ATOMIC_RELAXED, __HIP_MEMORY_SCOPE_AGENT); }
; __device__ __forceinline__ unsigned xb_add(unsigned* p, unsigned v) { return __hip_atomic_fetch_add(p, v, __ATOMIC_RELAXED, __HIP_MEMORY_SCOPE_AGENT); }
; #define XB_SPIN(cond, bar) do { unsigned _sp = 0; while (cond) { __builtin_amdgcn_s_sleep(1); \
;     if ((++_sp & 255u) == 0u) { if (xb_ld(&(bar)[XB_TMO])) break; if (_sp > XB_SPIN_CAP) { atomicAdd(&(bar)[XB_TMO], 1u); break; } } } } while (0)
; __device__ __forceinline__ void xcd_barrier(const XcdBarrier& b) {
;     ...
;         const unsigned old = xb_add(&bar[XB_XSUB(b.x)], 1u);
;         const unsigned gen = old / nloc;
;         if (old + 1u == (gen + 1u) * nloc) {
;             __builtin_amdgcn_fence(__ATOMIC_RELEASE, "agent");
;             asm volatile("s_waitcnt vmcnt(0)" ::: "memory");
;             const unsigned og = xb_add(&bar[XB_TOP], 1u);
;             const unsigned tg = og / nx;
;             if (og + 1u == (tg + 1u) * nx) xb_add(&bar[XB_TOPGEN], 1u);
;             else XB_SPIN(xb_ld(&bar[XB_TOPGEN]) == tg, bar);
;             __builtin_amdgcn_fence(__ATOMIC_ACQUIRE, "agent");
;             xb_add(&bar[XB_XGEN(b.x)], 1u);
;             asm volatile("s_waitcnt vmcnt(0)" ::: "memory");
;         } else {
;             XB_SPIN(xb_ld(&bar[XB_XGEN(b.x)]) == gen, bar);
;             __builtin_amdgcn_fence(__ATOMIC_ACQUIRE, "agent");
;             asm volatile("s_waitcnt vmcnt(0)" ::: "memory");
;         }
.LBB0_309:
	s_lshl_b32 s0, s33, 8
	v_readlane_b32 s4, v255, 1
	v_readlane_b32 s5, v255, 2
	s_add_u32 s10, s4, s0
	s_addc_u32 s11, s5, 0
	v_mov_b32_e32 v3, 0x1000
	v_mov_b32_e32 v4, 1
	global_atomic_add v3, v3, v4, s[10:11] offset:1024 sc0
	s_waitcnt lgkmcnt(0)
	v_readfirstlane_b32 s12, v2
	v_readfirstlane_b32 s13, v0
	s_mul_i32 s12, s12, 3
	s_mul_i32 s13, s13, 3
	v_mov_b32_e32 v1, 0xa2400
	v_mov_b32_e32 v6, 0x2400
	s_mov_b32 s1, 0
	s_waitcnt vmcnt(0)
	v_readfirstlane_b32 s0, v3
	s_add_i32 s0, s0, 1
	s_cmp_lg_u32 s0, s12
	s_cbranch_scc1 .Lgb3_poll
	global_atomic_add v1, v4, s[24:25] offset:0
	global_atomic_add v1, v4, s[24:25] offset:256
	global_atomic_add v1, v4, s[24:25] offset:512
	global_atomic_add v1, v4, s[24:25] offset:768
	global_atomic_add v1, v4, s[24:25] offset:1024
	global_atomic_add v1, v4, s[24:25] offset:1280
	global_atomic_add v1, v4, s[24:25] offset:1536
	global_atomic_add v1, v4, s[24:25] offset:1792
	global_atomic_add v1, v4, s[24:25] offset:2048
	global_atomic_add v1, v4, s[24:25] offset:2304
	global_atomic_add v1, v4, s[24:25] offset:2560
	global_atomic_add v1, v4, s[24:25] offset:2816
	global_atomic_add v1, v4, s[24:25] offset:3072
	global_atomic_add v1, v4, s[24:25] offset:3328
	global_atomic_add v1, v4, s[24:25] offset:3584
	global_atomic_add v1, v4, s[24:25] offset:3840

; __device__ __forceinline__ unsigned xb_ld(unsigned* p)              { return __hip_atomic_load(p, __ATOMIC_RELAXED, __HIP_MEMORY_SCOPE_AGENT); }
; __device__ __forceinline__ unsigned xb_add(unsigned* p, unsigned v) { return __hip_atomic_fetch_add(p, v, __ATOMIC_RELAXED, __HIP_MEMORY_SCOPE_AGENT); }
; #define XB_SPIN(cond, bar) do { unsigned _sp = 0; while (cond) { __builtin_amdgcn_s_sleep(1); \
;     if ((++_sp & 255u) == 0u) { if (xb_ld(&(bar)[XB_TMO])) break; if (_sp > XB_SPIN_CAP) { atomicAdd(&(bar)[XB_TMO], 1u); break; } } } } while (0)
; __device__ __forceinline__ void xcd_barrier(const XcdBarrier& b) {
;     ...
;         const unsigned old = xb_add(&bar[XB_XSUB(b.x)], 1u);
;         const unsigned gen = old / nloc;
;         if (old + 1u == (gen + 1u) * nloc) {
;             __builtin_amdgcn_fence(__ATOMIC_RELEASE, "agent");
;             asm volatile("s_waitcnt vmcnt(0)" ::: "memory");
;             const unsigned og = xb_add(&bar[XB_TOP], 1u);
;             const unsigned tg = og / nx;
;             if (og + 1u == (tg + 1u) * nx) xb_add(&bar[XB_TOPGEN], 1u);
;             else XB_SPIN(xb_ld(&bar[XB_TOPGEN]) == tg, bar);
;             __builtin_amdgcn_fence(__ATOMIC_ACQUIRE, "agent");
;             xb_add(&bar[XB_XGEN(b.x)], 1u);
;             asm volatile("s_waitcnt vmcnt(0)" ::: "memory");
;         } else {
;             XB_SPIN(xb_ld(&bar[XB_XGEN(b.x)]) == gen, bar);
;             __builtin_amdgcn_fence(__ATOMIC_ACQUIRE, "agent");
;             asm volatile("s_waitcnt vmcnt(0)" ::: "memory");
;         }
.LBB0_403:
	s_lshl_b32 s0, s33, 8
	v_readlane_b32 s4, v255, 1
	v_readlane_b32 s5, v255, 2
	s_add_u32 s10, s4, s0
	s_addc_u32 s11, s5, 0
	v_mov_b32_e32 v3, 0x1000
	v_mov_b32_e32 v4, 1
	global_atomic_add v3, v3, v4, s[10:11] offset:1024 sc0
	s_waitcnt lgkmcnt(0)
	v_readfirstlane_b32 s12, v2
	v_readfirstlane_b32 s13, v0
	s_mul_i32 s12, s12, 4
	s_mul_i32 s13, s13, 4
	v_mov_b32_e32 v1, 0xa2400
	v_mov_b32_e32 v6, 0x2400
	s_mov_b32 s1, 0
	s_waitcnt vmcnt(0)
	v_readfirstlane_b32 s0, v3
	s_add_i32 s0, s0, 1
	s_cmp_lg_u32 s0, s12
	s_cbranch_scc1 .Lgb4_poll
	buffer_wbl2 sc1
	s_waitcnt vmcnt(0)
	global_atomic_add v1, v4, s[24:25] offset:0
	global_atomic_add v1, v4, s[24:25] offset:256
	global_atomic_add v1, v4, s[24:25] offset:512
	global_atomic_add v1, v4, s[24:25] offset:768
	global_atomic_add v1, v4, s[24:25] offset:1024
	global_atomic_add v1, v4, s[24:25] offset:1280
	global_atomic_add v1, v4, s[24:25] offset:1536
	global_atomic_add v1, v4, s[24:25] offset:1792
	global_atomic_add v1, v4, s[24:25] offset:2048
	global_atomic_add v1, v4, s[24:25] offset:2304
	global_atomic_add v1, v4, s[24:25] offset:2560
	global_atomic_add v1, v4, s[24:25] offset:2816
	global_atomic_add v1, v4, s[24:25] offset:3072
	global_atomic_add v1, v4, s[24:25] offset:3328
	global_atomic_add v1, v4, s[24:25] offset:3584
	global_atomic_add v1, v4, s[24:25] offset:3840

; __device__ __forceinline__ unsigned xb_ld(unsigned* p)              { return __hip_atomic_load(p, __ATOMIC_RELAXED, __HIP_MEMORY_SCOPE_AGENT); }
; __device__ __forceinline__ unsigned xb_add(unsigned* p, unsigned v) { return __hip_atomic_fetch_add(p, v, __ATOMIC_RELAXED, __HIP_MEMORY_SCOPE_AGENT); }
; #define XB_SPIN(cond, bar) do { unsigned _sp = 0; while (cond) { __builtin_amdgcn_s_sleep(1); \
;     if ((++_sp & 255u) == 0u) { if (xb_ld(&(bar)[XB_TMO])) break; if (_sp > XB_SPIN_CAP) { atomicAdd(&(bar)[XB_TMO], 1u); break; } } } } while (0)
; __device__ __forceinline__ void xcd_barrier(const XcdBarrier& b) {
;     ...
;         const unsigned old = xb_add(&bar[XB_XSUB(b.x)], 1u);
;         const unsigned gen = old / nloc;
;         if (old + 1u == (gen + 1u) * nloc) {
;             __builtin_amdgcn_fence(__ATOMIC_RELEASE, "agent");
;             asm volatile("s_waitcnt vmcnt(0)" ::: "memory");
;             const unsigned og = xb_add(&bar[XB_TOP], 1u);
;             const unsigned tg = og / nx;
;             if (og + 1u == (tg + 1u) * nx) xb_add(&bar[XB_TOPGEN], 1u);
;             else XB_SPIN(xb_ld(&bar[XB_TOPGEN]) == tg, bar);
;             __builtin_amdgcn_fence(__ATOMIC_ACQUIRE, "agent");
;             xb_add(&bar[XB_XGEN(b.x)], 1u);
;             asm volatile("s_waitcnt vmcnt(0)" ::: "memory");
;         } else {
;             XB_SPIN(xb_ld(&bar[XB_XGEN(b.x)]) == gen, bar);
;             __builtin_amdgcn_fence(__ATOMIC_ACQUIRE, "agent");
;             asm volatile("s_waitcnt vmcnt(0)" ::: "memory");
;         }
.LBB0_513:
	s_lshl_b32 s0, s33, 8
	v_readlane_b32 s4, v255, 1
	v_readlane_b32 s5, v255, 2
	s_add_u32 s10, s4, s0
	s_addc_u32 s11, s5, 0
	v_mov_b32_e32 v3, 0x1000
	v_mov_b32_e32 v4, 1
	global_atomic_add v3, v3, v4, s[10:11] offset:1024 sc0
	s_waitcnt lgkmcnt(0)
	v_readfirstlane_b32 s12, v2
	v_readfirstlane_b32 s13, v0
	s_mul_i32 s12, s12, 5
	s_mul_i32 s13, s13, 5
	v_mov_b32_e32 v1, 0xa2400
	v_mov_b32_e32 v6, 0x2400
	s_mov_b32 s1, 0
	s_waitcnt vmcnt(0)
	v_readfirstlane_b32 s0, v3
	s_add_i32 s0, s0, 1
	s_cmp_lg_u32 s0, s12
	s_cbranch_scc1 .Lgb5_poll
	global_atomic_add v1, v4, s[24:25] offset:0
	global_atomic_add v1, v4, s[24:25] offset:256
	global_atomic_add v1, v4, s[24:25] offset:512
	global_atomic_add v1, v4, s[24:25] offset:768
	global_atomic_add v1, v4, s[24:25] offset:1024
	global_atomic_add v1, v4, s[24:25] offset:1280
	global_atomic_add v1, v4, s[24:25] offset:1536
	global_atomic_add v1, v4, s[24:25] offset:1792
	global_atomic_add v1, v4, s[24:25] offset:2048
	global_atomic_add v1, v4, s[24:25] offset:2304
	global_atomic_add v1, v4, s[24:25] offset:2560
	global_atomic_add v1, v4, s[24:25] offset:2816
	global_atomic_add v1, v4, s[24:25] offset:3072
	global_atomic_add v1, v4, s[24:25] offset:3328
	global_atomic_add v1, v4, s[24:25] offset:3584
	global_atomic_add v1, v4, s[24:25] offset:3840

; __device__ __forceinline__ unsigned xb_ld(unsigned* p)              { return __hip_atomic_load(p, __ATOMIC_RELAXED, __HIP_MEMORY_SCOPE_AGENT); }
; __device__ __forceinline__ unsigned xb_add(unsigned* p, unsigned v) { return __hip_atomic_fetch_add(p, v, __ATOMIC_RELAXED, __HIP_MEMORY_SCOPE_AGENT); }
; #define XB_SPIN(cond, bar) do { unsigned _sp = 0; while (cond) { __builtin_amdgcn_s_sleep(1); \
;     if ((++_sp & 255u) == 0u) { if (xb_ld(&(bar)[XB_TMO])) break; if (_sp > XB_SPIN_CAP) { atomicAdd(&(bar)[XB_TMO], 1u); break; } } } } while (0)
; __device__ __forceinline__ void xcd_barrier(const XcdBarrier& b) {
;     ...
;         const unsigned old = xb_add(&bar[XB_XSUB(b.x)], 1u);
;         const unsigned gen = old / nloc;
;         if (old + 1u == (gen + 1u) * nloc) {
;             __builtin_amdgcn_fence(__ATOMIC_RELEASE, "agent");
;             asm volatile("s_waitcnt vmcnt(0)" ::: "memory");
;             const unsigned og = xb_add(&bar[XB_TOP], 1u);
;             const unsigned tg = og / nx;
;             if (og + 1u == (tg + 1u) * nx) xb_add(&bar[XB_TOPGEN], 1u);
;             else XB_SPIN(xb_ld(&bar[XB_TOPGEN]) == tg, bar);
;             __builtin_amdgcn_fence(__ATOMIC_ACQUIRE, "agent");
;             xb_add(&bar[XB_XGEN(b.x)], 1u);
;             asm volatile("s_waitcnt vmcnt(0)" ::: "memory");
;         } else {
;             XB_SPIN(xb_ld(&bar[XB_XGEN(b.x)]) == gen, bar);
;             __builtin_amdgcn_fence(__ATOMIC_ACQUIRE, "agent");
;             asm volatile("s_waitcnt vmcnt(0)" ::: "memory");
;         }
.LBB0_617:
	s_lshl_b32 s0, s33, 8
	v_readlane_b32 s4, v255, 1
	v_readlane_b32 s5, v255, 2
	s_add_u32 s10, s4, s0
	s_addc_u32 s11, s5, 0
	v_mov_b32_e32 v3, 0x1000
	v_mov_b32_e32 v4, 1
	global_atomic_add v3, v3, v4, s[10:11] offset:1024 sc0
	s_waitcnt lgkmcnt(0)
	v_readfirstlane_b32 s12, v2
	v_readfirstlane_b32 s13, v0
	s_mul_i32 s12, s12, 6
	s_mul_i32 s13, s13, 6
	v_mov_b32_e32 v1, 0xa2400
	v_mov_b32_e32 v6, 0x2400
	s_mov_b32 s1, 0
	s_waitcnt vmcnt(0)
	v_readfirstlane_b32 s0, v3
	s_add_i32 s0, s0, 1
	s_cmp_lg_u32 s0, s12
	s_cbranch_scc1 .Lgb6_poll
	buffer_wbl2 sc1
	s_waitcnt vmcnt(0)
	global_atomic_add v1, v4, s[24:25] offset:0
	global_atomic_add v1, v4, s[24:25] offset:256
	global_atomic_add v1, v4, s[24:25] offset:512
	global_atomic_add v1, v4, s[24:25] offset:768
	global_atomic_add v1, v4, s[24:25] offset:1024
	global_atomic_add v1, v4, s[24:25] offset:1280
	global_atomic_add v1, v4, s[24:25] offset:1536
	global_atomic_add v1, v4, s[24:25] offset:1792
	global_atomic_add v1, v4, s[24:25] offset:2048
	global_atomic_add v1, v4, s[24:25] offset:2304
	global_atomic_add v1, v4, s[24:25] offset:2560
	global_atomic_add v1, v4, s[24:25] offset:2816
	global_atomic_add v1, v4, s[24:25] offset:3072
	global_atomic_add v1, v4, s[24:25] offset:3328
	global_atomic_add v1, v4, s[24:25] offset:3584
	global_atomic_add v1, v4, s[24:25] offset:3840
